# LRU loops + merge gate epilogue rewritten, attention row-max via v_max3, SSD dt loads hoisted
# baseline (speedup 1.0000x reference)
; __device__ __forceinline__ void ssd_mfma(PP P, int l, unsigned char* ws, LAS unsigned char* lds, int unit, int wave, int tid_) {
;     ...
;             SSD_STAGE(ck + 1);
;             if (ck + 2 < 32) { SSD_LOAD(ck + 2); if (wave == 7) SSD_FCALC(ck + 2); }
.LBB0_1201:
	s_add_i32 s1, s0, 1
	s_cmp_eq_u32 s0, 31
	s_cbranch_scc1 .LBB0_1124
	s_and_b64 vcc, exec, s[44:45]
	s_cbranch_vccnz .Lssd_fc_skip
	s_cmp_gt_u32 s0, 29
	s_cbranch_scc1 .Lssd_fc_skip
	s_add_i32 s28, s36, 0x100
	v_readlane_b32 vcc_lo, v254, 46
	v_readlane_b32 vcc_hi, v254, 47
	s_add_u32 vcc_lo, vcc_lo, s28
	s_addc_u32 vcc_hi, vcc_hi, 0
	v_mov_b32_e32 v203, vcc_hi
	v_or_b32_e32 v202, vcc_lo, v92
	v_readlane_b32 s28, v255, 59
	v_lshlrev_b64 v[202:203], 5, v[202:203]
	v_readlane_b32 s29, v255, 60
	v_readlane_b32 vcc_lo, v254, 19
	s_nop 1
	v_lshl_add_u64 v[204:205], s[28:29], 0, v[202:203]
	v_readlane_b32 s28, v255, 55
	v_lshl_or_b32 v202, vcc_lo, 2, v202
	v_readlane_b32 s29, v255, 56
	s_nop 1
	global_load_dword v200, v[204:205], off
	s_nop 0
	v_lshl_add_u64 v[202:203], s[28:29], 0, v[202:203]
	global_load_dword v201, v[202:203], off
.Lssd_fc_skip:
	s_lshl_b32 s28, s1, 11
	s_and_b32 s28, s28, 0x800
	v_add_u32_e32 v0, s28, v94
	ds_read2st64_b32 v[22:23], v0 offset0:2 offset1:4
	ds_read_b32 v0, v0 offset:1536
	v_lshlrev_b32_e32 v18, 16, v38
	v_and_b32_e32 v19, 0xffff0000, v38
	v_lshlrev_b32_e32 v20, 16, v39
	v_and_b32_e32 v21, 0xffff0000, v39
	s_waitcnt lgkmcnt(1)
	v_pk_mul_f32 v[18:19], v[22:23], v[18:19] op_sel_hi:[0,1]
	v_lshlrev_b32_e32 v24, 16, v40
	v_and_b32_e32 v25, 0xffff0000, v40
	v_lshlrev_b32_e32 v26, 16, v41
	v_and_b32_e32 v27, 0xffff0000, v41
	v_lshlrev_b32_e32 v28, 16, v34
	v_and_b32_e32 v29, 0xffff0000, v34
	v_pk_mul_f32 v[20:21], v[22:23], v[20:21] op_sel_hi:[0,1]
	v_cvt_pk_bf16_f32 v18, v18, v19
	v_cvt_pk_bf16_f32 v19, v20, v21
	ds_write_b128 v95, v[38:41]
	ds_write_b128 v95, v[34:37] offset:16
	ds_write_b128 v95, v[46:49] offset:18432
	ds_write_b128 v95, v[42:45] offset:18448
	v_lshlrev_b32_e32 v30, 16, v35
	v_and_b32_e32 v31, 0xffff0000, v35
	v_pk_mul_f32 v[26:27], v[22:23], v[26:27] op_sel_hi:[0,1]
	v_pk_mul_f32 v[24:25], v[22:23], v[24:25] op_sel_hi:[0,1]
	v_cvt_pk_bf16_f32 v20, v24, v25
	v_cvt_pk_bf16_f32 v21, v26, v27
	ds_write_b128 v96, v[18:21] offset:256
	v_pk_mul_f32 v[18:19], v[22:23], v[28:29] op_sel_hi:[0,1]
	v_lshlrev_b32_e32 v32, 16, v36
	v_and_b32_e32 v33, 0xffff0000, v36
	v_lshlrev_b32_e32 v72, 16, v37
	v_and_b32_e32 v73, 0xffff0000, v37
	v_pk_mul_f32 v[20:21], v[22:23], v[30:31] op_sel_hi:[0,1]
	v_cvt_pk_bf16_f32 v18, v18, v19
	v_pk_mul_f32 v[24:25], v[22:23], v[72:73] op_sel_hi:[0,1]
	v_pk_mul_f32 v[26:27], v[22:23], v[32:33] op_sel_hi:[0,1]
	v_cvt_pk_bf16_f32 v19, v20, v21
	v_cvt_pk_bf16_f32 v20, v26, v27
	v_cvt_pk_bf16_f32 v21, v24, v25
	ds_write_b128 v96, v[18:21] offset:272
	v_lshlrev_b32_e32 v18, 16, v46
	v_mul_f32_e32 v18, v23, v18
	v_lshlrev_b32_e32 v22, 16, v48
	v_cvt_pk_bf16_f32 v18, v18, v1
	ds_write_b16 v97, v18 offset:62464
	v_mul_f32_e32 v18, v23, v22
	v_lshlrev_b32_e32 v27, 16, v42
	v_cvt_pk_bf16_f32 v18, v18, v1
	ds_write_b16 v97, v18 offset:63552
	v_mul_f32_e32 v18, v23, v27
	v_lshlrev_b32_e32 v31, 16, v44
	v_cvt_pk_bf16_f32 v18, v18, v1
	ds_write_b16 v97, v18 offset:64640
	v_mul_f32_e32 v18, v23, v31
	v_lshlrev_b32_e32 v72, 16, v54
	v_cvt_pk_bf16_f32 v18, v18, v1
	ds_write_b16 v98, v18 offset:3264
	s_waitcnt lgkmcnt(10)
	v_mul_f32_e32 v18, v0, v72
	v_lshlrev_b32_e32 v76, 16, v56
	v_cvt_pk_bf16_f32 v18, v18, v1
	ds_write_b16 v99, v18 offset:36864
	v_mul_f32_e32 v18, v0, v76
	v_lshlrev_b32_e32 v80, 16, v50
	v_cvt_pk_bf16_f32 v18, v18, v1
	ds_write_b16 v99, v18 offset:38464
	v_mul_f32_e32 v18, v0, v80
	v_lshlrev_b32_e32 v84, 16, v52
	v_cvt_pk_bf16_f32 v18, v18, v1
	ds_write_b16 v99, v18 offset:40064
	v_mul_f32_e32 v18, v0, v84
	v_and_b32_e32 v19, 0xffff0000, v46
	v_cvt_pk_bf16_f32 v18, v18, v1
	ds_write_b16 v99, v18 offset:41664
	v_mul_f32_e32 v18, v23, v19
	v_and_b32_e32 v24, 0xffff0000, v48
	v_cvt_pk_bf16_f32 v18, v18, v1
	ds_write_b16 v97, v18 offset:62736
	v_mul_f32_e32 v18, v23, v24
	v_and_b32_e32 v28, 0xffff0000, v42
	v_cvt_pk_bf16_f32 v18, v18, v1
	ds_write_b16 v97, v18 offset:63824
	v_mul_f32_e32 v18, v23, v28
	v_and_b32_e32 v32, 0xffff0000, v44
	v_cvt_pk_bf16_f32 v18, v18, v1
	ds_write_b16 v97, v18 offset:64912
	v_mul_f32_e32 v18, v23, v32
	v_and_b32_e32 v73, 0xffff0000, v54
	v_cvt_pk_bf16_f32 v18, v18, v1
	ds_write_b16 v98, v18 offset:3536
	v_mul_f32_e32 v18, v0, v73
	v_and_b32_e32 v77, 0xffff0000, v56
	v_cvt_pk_bf16_f32 v18, v18, v1
	ds_write_b16 v99, v18 offset:37264
	v_mul_f32_e32 v18, v0, v77
	v_and_b32_e32 v81, 0xffff0000, v50
	v_cvt_pk_bf16_f32 v18, v18, v1
	ds_write_b16 v99, v18 offset:38864
	v_mul_f32_e32 v18, v0, v81
	v_and_b32_e32 v85, 0xffff0000, v52
	v_cvt_pk_bf16_f32 v18, v18, v1
	ds_write_b16 v99, v18 offset:40464
	v_mul_f32_e32 v18, v0, v85
	v_lshlrev_b32_e32 v20, 16, v47
	v_cvt_pk_bf16_f32 v18, v18, v1
	ds_write_b16 v99, v18 offset:42064
	v_mul_f32_e32 v18, v23, v20
	v_lshlrev_b32_e32 v25, 16, v49
	v_cvt_pk_bf16_f32 v18, v18, v1
	ds_write_b16 v97, v18 offset:63008
	v_mul_f32_e32 v18, v23, v25
	v_lshlrev_b32_e32 v29, 16, v43
	v_cvt_pk_bf16_f32 v18, v18, v1
	ds_write_b16 v97, v18 offset:64096
	v_mul_f32_e32 v18, v23, v29
	v_lshlrev_b32_e32 v33, 16, v45
	v_cvt_pk_bf16_f32 v18, v18, v1
	ds_write_b16 v97, v18 offset:65184
	v_mul_f32_e32 v18, v23, v33
	v_lshlrev_b32_e32 v74, 16, v55
	v_cvt_pk_bf16_f32 v18, v18, v1
	ds_write_b16 v98, v18 offset:3808
	v_mul_f32_e32 v18, v0, v74
	v_lshlrev_b32_e32 v78, 16, v57
	v_cvt_pk_bf16_f32 v18, v18, v1
	ds_write_b16 v99, v18 offset:37664
	v_mul_f32_e32 v18, v0, v78
	v_lshlrev_b32_e32 v82, 16, v51
	v_cvt_pk_bf16_f32 v18, v18, v1
	ds_write_b16 v99, v18 offset:39264
	v_mul_f32_e32 v18, v0, v82
	v_lshlrev_b32_e32 v86, 16, v53
	v_cvt_pk_bf16_f32 v18, v18, v1
	ds_write_b16 v99, v18 offset:40864
	v_mul_f32_e32 v18, v0, v86
	v_and_b32_e32 v21, 0xffff0000, v47
	v_cvt_pk_bf16_f32 v18, v18, v1
	ds_write_b16 v99, v18 offset:42464
	v_mul_f32_e32 v18, v23, v21
	v_and_b32_e32 v26, 0xffff0000, v49
	v_cvt_pk_bf16_f32 v18, v18, v1
	ds_write_b16 v97, v18 offset:63280
	v_mul_f32_e32 v18, v23, v26
	v_and_b32_e32 v30, 0xffff0000, v43
	v_cvt_pk_bf16_f32 v18, v18, v1
	ds_write_b16 v97, v18 offset:64368
	v_mul_f32_e32 v18, v23, v30
	v_and_b32_e32 v58, 0xffff0000, v45
	v_cvt_pk_bf16_f32 v18, v18, v1
	ds_write_b16 v97, v18 offset:65456
	v_mul_f32_e32 v18, v23, v58
	v_and_b32_e32 v75, 0xffff0000, v55
	v_cvt_pk_bf16_f32 v18, v18, v1
	ds_write_b16 v98, v18 offset:4080
	v_mul_f32_e32 v18, v0, v75
	v_and_b32_e32 v79, 0xffff0000, v57
	v_cvt_pk_bf16_f32 v18, v18, v1
	ds_write_b16 v99, v18 offset:38064
	v_mul_f32_e32 v18, v0, v79
	v_and_b32_e32 v83, 0xffff0000, v51
	v_and_b32_e32 v87, 0xffff0000, v53
	v_cvt_pk_bf16_f32 v18, v18, v1
	ds_write_b16 v99, v18 offset:39664
	v_mul_f32_e32 v18, v0, v83
	v_mul_f32_e32 v0, v0, v87
	s_cmp_gt_u32 s0, 29
	v_cvt_pk_bf16_f32 v18, v18, v1
	ds_write_b16 v99, v18 offset:41264
	v_cvt_pk_bf16_f32 v0, v0, v1
	ds_write_b16 v99, v0 offset:42864
	s_cbranch_scc1 .LBB0_1124
	s_add_i32 s0, s36, 0x100
	v_readlane_b32 s28, v254, 46
	v_readlane_b32 s29, v254, 47
	s_add_u32 s28, s28, s0
	s_addc_u32 s29, s29, 0
	v_lshl_add_u64 v[18:19], s[28:29], 0, v[60:61]
	v_lshlrev_b64 v[20:21], 9, v[18:19]
	v_lshl_add_u64 v[20:21], v[68:69], 0, v[20:21]
	global_load_dwordx4 v[34:37], v[20:21], off offset:272
	global_load_dwordx4 v[38:41], v[20:21], off offset:256
	global_load_dwordx4 v[42:45], v[20:21], off offset:16
	global_load_dwordx4 v[46:49], v[20:21], off
	v_lshlrev_b64 v[18:19], 12, v[18:19]
	v_lshl_add_u64 v[18:19], v[70:71], 0, v[18:19]
	global_load_dwordx4 v[50:53], v[18:19], off offset:2064
	global_load_dwordx4 v[54:57], v[18:19], off offset:2048
	s_and_b64 vcc, exec, s[44:45]
	s_cbranch_vccnz .LBB0_1124
	v_add_u32_e32 v22, -1, v226
	v_and_b32_e32 v21, 64, v226
	v_cmp_lt_i32_e32 vcc, v22, v21
	s_waitcnt vmcnt(6)
	v_mov_b32_e32 v0, v200
	v_mov_b32_e32 v18, v201
	v_mul_f32_e64 v19, v0, -v93
	v_cndmask_b32_e32 v22, v22, v226, vcc
	v_lshlrev_b32_e32 v22, 2, v22
	v_mul_f32_e64 v20, v18, -v93
	ds_bpermute_b32 v23, v22, v19
	ds_bpermute_b32 v22, v22, v20
	s_waitcnt lgkmcnt(1)
	v_fma_f32 v23, v0, -v93, v23
	s_waitcnt lgkmcnt(0)
	v_fma_f32 v22, v18, -v93, v22
	v_cndmask_b32_e64 v20, v22, v20, s[18:19]
	v_add_u32_e32 v22, -2, v226
	v_cmp_lt_i32_e32 vcc, v22, v21
	v_cndmask_b32_e64 v19, v23, v19, s[18:19]
	s_nop 0
	v_cndmask_b32_e32 v22, v22, v226, vcc
	v_lshlrev_b32_e32 v22, 2, v22
	ds_bpermute_b32 v23, v22, v19
	ds_bpermute_b32 v22, v22, v20
	s_waitcnt lgkmcnt(1)
	v_add_f32_e32 v23, v19, v23
	s_waitcnt lgkmcnt(0)
	v_add_f32_e32 v22, v20, v22
	v_cndmask_b32_e64 v20, v22, v20, s[20:21]
	v_add_u32_e32 v22, -4, v226
	v_cmp_lt_i32_e32 vcc, v22, v21
	v_cndmask_b32_e64 v19, v23, v19, s[20:21]
	s_nop 0
	v_cndmask_b32_e32 v22, v22, v226, vcc
	v_lshlrev_b32_e32 v22, 2, v22
	ds_bpermute_b32 v23, v22, v19
	ds_bpermute_b32 v22, v22, v20
	s_waitcnt lgkmcnt(1)
	v_add_f32_e32 v23, v19, v23
	s_waitcnt lgkmcnt(0)
	v_add_f32_e32 v22, v20, v22
	v_cndmask_b32_e64 v20, v22, v20, s[22:23]
	v_add_u32_e32 v22, -8, v226
	v_cmp_lt_i32_e32 vcc, v22, v21
	v_cndmask_b32_e64 v19, v23, v19, s[22:23]
	s_nop 0
	v_cndmask_b32_e32 v22, v22, v226, vcc
	v_lshlrev_b32_e32 v22, 2, v22
	ds_bpermute_b32 v23, v22, v19
	ds_bpermute_b32 v22, v22, v20
	s_waitcnt lgkmcnt(1)
	v_add_f32_e32 v23, v19, v23
	s_waitcnt lgkmcnt(0)
	v_add_f32_e32 v22, v20, v22
	v_cndmask_b32_e64 v20, v22, v20, s[24:25]
	v_add_u32_e32 v22, -16, v226
	v_cmp_lt_i32_e32 vcc, v22, v21
	v_cndmask_b32_e64 v19, v23, v19, s[24:25]
	s_nop 0
	v_cndmask_b32_e32 v22, v22, v226, vcc
	v_lshlrev_b32_e32 v22, 2, v22
	ds_bpermute_b32 v23, v22, v19
	ds_bpermute_b32 v22, v22, v20
	s_waitcnt lgkmcnt(1)
	v_add_f32_e32 v23, v19, v23
	s_waitcnt lgkmcnt(0)
	v_add_f32_e32 v22, v20, v22
	v_cndmask_b32_e64 v20, v22, v20, s[26:27]
	v_subrev_u32_e32 v22, 32, v226
	v_cmp_lt_i32_e32 vcc, v22, v21
	v_cndmask_b32_e64 v19, v23, v19, s[26:27]
	s_nop 0
	v_cndmask_b32_e32 v21, v22, v226, vcc
	v_lshlrev_b32_e32 v21, 2, v21
	ds_bpermute_b32 v22, v21, v19
	ds_bpermute_b32 v21, v21, v20
	s_waitcnt lgkmcnt(1)
	v_add_f32_e32 v22, v19, v22
	s_waitcnt lgkmcnt(0)
	v_add_f32_e32 v21, v20, v21
	v_cndmask_b32_e64 v20, v21, v20, s[46:47]
	v_bfrev_b32_e32 v21, 0.5
	v_cndmask_b32_e64 v19, v22, v19, s[46:47]
	v_lshl_or_b32 v21, v226, 2, v21
	ds_bpermute_b32 v22, v21, v19
	v_mul_f32_e32 v23, 0x3fb8aa3b, v19
	v_exp_f32_e32 v23, v23
	s_waitcnt lgkmcnt(0)
	v_add_f32_e32 v20, v20, v22
	ds_bpermute_b32 v21, v21, v20
	v_lshl_add_u32 v22, v92, 2, s31
	ds_write2st64_b32 v22, v19, v20 offset1:1
	v_mul_f32_e32 v24, 0x3fb8aa3b, v20
	v_exp_f32_e32 v24, v24
	s_waitcnt lgkmcnt(1)
	v_sub_f32_e32 v19, v21, v19
	v_sub_f32_e32 v20, v21, v20
	v_mul_f32_e32 v19, 0x3fb8aa3b, v19
	v_mul_f32_e32 v20, 0x3fb8aa3b, v20
	v_exp_f32_e32 v19, v19
	v_exp_f32_e32 v20, v20
	ds_write2st64_b32 v22, v23, v24 offset0:2 offset1:3
	ds_write2st64_b32 v22, v19, v20 offset0:4 offset1:5
	ds_write2st64_b32 v22, v0, v18 offset0:6 offset1:7
	s_branch .LBB0_1124

; __device__ __forceinline__ float xhalf_max(float v) { const auto r_ = __builtin_amdgcn_permlane32_swap(__float_as_uint(v), __float_as_uint(v), false, false); return fmaxf(__uint_as_float(r_[0]), __uint_as_float(r_[1])); }
; __device__ __forceinline__ void attn_unit(unsigned char* ws, LAS unsigned char* lds, int b, int h, int qb, int wave, int tid_, bf16_t* Obase, int opitch) {
;     ...
;             float tm = fmaxf(p0[0], p1[0]);
; #pragma unroll
;             for (int i = 1; i < 16; ++i) tm = fmaxf(tm, fmaxf(p0[i], p1[i]));
;             tm = xhalf_max(tm);
;             if (__any(tm > mx + 8.f)) {
;                 const float mn = fmaxf(mx, tm);
;                 const float alpha = __builtin_amdgcn_exp2f(mx - mn);
;                 mx = mn; lsum *= alpha;
; #pragma unroll
;                 for (int i = 0; i < 16; ++i) { o0[i] *= alpha; o1[i] *= alpha; }
;             }
.LBB0_1244:
	s_nop 10
	v_max3_f32 v0, v34, v35, v36
	v_max3_f32 v112, v37, v38, v39
	v_max3_f32 v113, v40, v41, v42
	v_max3_f32 v114, v43, v44, v45
	v_max3_f32 v0, v0, v46, v47
	v_max3_f32 v112, v112, v48, v49
	v_max3_f32 v113, v113, v50, v51
	v_max3_f32 v114, v114, v52, v53
	v_max3_f32 v0, v0, v54, v55
	v_max3_f32 v112, v112, v56, v57
	v_max3_f32 v113, v113, v58, v59
	v_max3_f32 v114, v114, v60, v61
	v_max3_f32 v0, v0, v62, v63
	v_max3_f32 v112, v112, v64, v65
	v_max3_f32 v0, v0, v112, v113
	v_max_f32_e32 v0, v0, v114
	v_mov_b32_e32 v112, v0
	s_nop 1
	v_permlane32_swap_b32_e32 v0, v112
	v_max_f32_e32 v112, v112, v112
	v_max_f32_e32 v0, v0, v0
	v_max_f32_e32 v0, v0, v112
	v_add_f32_e32 v112, 0x41000000, v126
	v_cmp_gt_f32_e32 vcc, v0, v112
	s_cbranch_vccz .LBB0_1246
	v_max_f32_e32 v0, v0, v0
	v_max_f32_e32 v112, v126, v126
	v_max_f32_e32 v112, v112, v0
	v_sub_f32_e32 v0, v126, v112
	v_exp_f32_e32 v0, v0
	v_mov_b32_e32 v126, v112
	v_pk_mul_f32 v[32:33], v[32:33], v[0:1] op_sel_hi:[1,0]
	v_pk_mul_f32 v[30:31], v[30:31], v[0:1] op_sel_hi:[1,0]
	v_pk_mul_f32 v[28:29], v[28:29], v[0:1] op_sel_hi:[1,0]
	v_pk_mul_f32 v[26:27], v[26:27], v[0:1] op_sel_hi:[1,0]
	v_pk_mul_f32 v[24:25], v[24:25], v[0:1] op_sel_hi:[1,0]
	v_pk_mul_f32 v[22:23], v[22:23], v[0:1] op_sel_hi:[1,0]
	v_pk_mul_f32 v[20:21], v[20:21], v[0:1] op_sel_hi:[1,0]
	v_pk_mul_f32 v[18:19], v[18:19], v[0:1] op_sel_hi:[1,0]
	v_pk_mul_f32 v[16:17], v[16:17], v[0:1] op_sel_hi:[1,0]
	v_pk_mul_f32 v[14:15], v[14:15], v[0:1] op_sel_hi:[1,0]
	v_pk_mul_f32 v[12:13], v[12:13], v[0:1] op_sel_hi:[1,0]
	v_pk_mul_f32 v[10:11], v[10:11], v[0:1] op_sel_hi:[1,0]
	v_pk_mul_f32 v[8:9], v[8:9], v[0:1] op_sel_hi:[1,0]
	v_pk_mul_f32 v[6:7], v[6:7], v[0:1] op_sel_hi:[1,0]
	v_pk_mul_f32 v[4:5], v[4:5], v[0:1] op_sel_hi:[1,0]
	v_pk_mul_f32 v[2:3], v[2:3], v[0:1] op_sel_hi:[1,0]
	v_mul_f32_e32 v125, v125, v0
